# barrier L1 invalidate moved from leader thread to wave 1 at barrier entry (runs concurrently with the arrival protocol)
# speedup vs baseline: 1.3230x; 1.3230x over previous
.LBB0_50:
	s_waitcnt vmcnt(0)
	s_barrier
	v_readfirstlane_b32 s98, v0
	s_lshr_b32 s98, s98, 6
	s_cmp_lg_u32 s98, 1
	s_cbranch_scc1 .Linv_skip_1
	buffer_inv sc1
	s_waitcnt vmcnt(0)
.Linv_skip_1:
	s_and_saveexec_b64 s[18:19], s[44:45]
	s_cbranch_execz .LBB0_132
	s_add_i32 s4, 0, 0x24160
	v_mov_b32_e32 v1, s4
	s_waitcnt vmcnt(0) expcnt(0) lgkmcnt(0)
	ds_read_b32 v10, v1
	s_add_i32 s4, 0, 0x24164
	v_mov_b32_e32 v1, s4
	ds_read_b32 v9, v1
	s_waitcnt lgkmcnt(1)
	v_cmp_ne_u32_e32 vcc, 0, v10
	s_cbranch_vccnz .LBB0_66
	v_readlane_b32 s4, v254, 0
	v_readlane_b32 s5, v254, 1
	s_load_dwordx2 s[6:7], s[4:5], 0x4
	s_add_u32 s20, s46, 0x4200
	s_addc_u32 s21, s47, 0
	s_add_u32 s4, s46, 0x4400
	s_addc_u32 s5, s47, 0
	s_waitcnt lgkmcnt(0)
	s_mul_i32 s50, s6, s3
	s_add_u32 s6, s46, 0x4500
	s_mul_i32 s50, s50, s7
	s_addc_u32 s7, s47, 0
	s_add_u32 s8, s46, 0x4600
	s_addc_u32 s9, s47, 0
	s_add_u32 s10, s46, 0x4700
	s_addc_u32 s11, s47, 0
	s_add_u32 s12, s46, 0x4800
	s_addc_u32 s13, s47, 0
	s_add_u32 s14, s46, 0x4900
	s_addc_u32 s15, s47, 0
	s_add_u32 s16, s46, 0x4a00
	s_addc_u32 s17, s47, 0
	s_add_u32 s22, s46, 0x4b00
	s_addc_u32 s23, s47, 0
	s_add_u32 s26, s46, 0x4c00
	s_addc_u32 s27, s47, 0
	s_add_u32 s28, s46, 0x4d00
	s_addc_u32 s29, s47, 0
	s_add_u32 s30, s46, 0x4e00
	s_addc_u32 s31, s47, 0
	s_add_u32 s34, s46, 0x4f00
	s_addc_u32 s35, s47, 0
	s_add_u32 s36, s46, 0x5000
	s_addc_u32 s37, s47, 0
	s_add_u32 s38, s46, 0x5100
	s_addc_u32 s39, s47, 0
	s_add_u32 s40, s46, 0x5200
	s_addc_u32 s41, s47, 0
	s_add_u32 s42, s46, 0x5300
	s_addc_u32 s43, s47, 0
	s_mov_b32 s51, 1
	v_mov_b32_e32 v17, 0
	s_branch .LBB0_54

.LBB0_81:
	s_or_b64 exec, exec, s[8:9]
	s_waitcnt vmcnt(0) lgkmcnt(0)
	s_waitcnt vmcnt(0)

.LBB0_131:
	s_or_b64 exec, exec, s[4:5]
	s_waitcnt vmcnt(0)
	s_waitcnt vmcnt(0)

.LBB0_138:
	v_cndmask_b32_e64 v2, 0, 1, s[26:27]
	v_cmp_ne_u32_e64 s[4:5], 1, v2
	s_andn2_b64 vcc, exec, s[26:27]
	s_mov_b64 s[6:7], -1
	s_cbranch_vccnz .LBB0_158
	s_waitcnt vmcnt(0)
	s_barrier
	v_readfirstlane_b32 s98, v0
	s_lshr_b32 s98, s98, 6
	s_cmp_lg_u32 s98, 1
	s_cbranch_scc1 .Linv_skip_2
	buffer_inv sc1
	s_waitcnt vmcnt(0)
.Linv_skip_2:
	s_and_saveexec_b64 s[6:7], s[44:45]
	s_cbranch_execz .LBB0_157
	s_add_i32 s8, 0, 0x24160
	v_mov_b32_e32 v2, s8
	s_waitcnt vmcnt(0) expcnt(0) lgkmcnt(0)
	ds_read_b32 v2, v2
	s_mov_b64 s[10:11], exec
	s_lshl_b32 s8, s33, 8
	v_mbcnt_lo_u32_b32 v3, s10, 0
	s_add_u32 s8, s48, s8
	v_mbcnt_hi_u32_b32 v3, s11, v3
	s_addc_u32 s9, s49, 0
	v_cmp_eq_u32_e32 vcc, 0, v3
	s_and_saveexec_b64 s[12:13], vcc
	s_cbranch_execz .LBB0_142
	s_bcnt1_i32_b64 s10, s[10:11]
	v_mov_b32_e32 v4, 0x3000
	v_mov_b32_e32 v5, s10
	global_atomic_add v4, v4, v5, s[8:9] offset:1536 sc0
.LBB0_142:
	s_or_b64 exec, exec, s[12:13]
	s_waitcnt lgkmcnt(0)
	v_cvt_f32_u32_e32 v5, v2
	s_waitcnt vmcnt(0)
	v_readfirstlane_b32 s10, v4
	s_mov_b64 s[12:13], -1
	v_rcp_iflag_f32_e32 v5, v5
	v_add_u32_e32 v3, s10, v3
	v_add_u32_e32 v6, 1, v3
	s_add_u32 s10, s8, 0x4600
	v_mul_f32_e32 v4, 0x4f7ffffe, v5
	v_cvt_u32_f32_e32 v4, v4
	v_sub_u32_e32 v5, 0, v2
	s_addc_u32 s11, s9, 0
	v_mul_lo_u32 v5, v5, v4
	v_mul_hi_u32 v5, v4, v5
	v_add_u32_e32 v4, v4, v5
	v_mul_hi_u32 v4, v3, v4
	v_mul_lo_u32 v5, v4, v2
	v_sub_u32_e32 v3, v3, v5
	v_add_u32_e32 v7, 1, v4
	v_cmp_ge_u32_e32 vcc, v3, v2
	v_sub_u32_e32 v5, v3, v2
	s_nop 0
	v_cndmask_b32_e32 v4, v4, v7, vcc
	v_cndmask_b32_e32 v3, v3, v5, vcc
	v_add_u32_e32 v5, 1, v4
	v_cmp_ge_u32_e32 vcc, v3, v2
	s_nop 1
	v_cndmask_b32_e32 v4, v4, v5, vcc
	v_mul_lo_u32 v3, v2, v4
	v_add_u32_e32 v2, v3, v2
	v_cmp_ne_u32_e32 vcc, v6, v2
	v_mov_b64_e32 v[2:3], s[10:11]
	s_and_saveexec_b64 s[8:9], vcc
	s_cbranch_execz .LBB0_154
	v_mov_b32_e32 v2, 0
	global_load_dword v3, v2, s[10:11] sc1
	s_mov_b64 s[16:17], 0
	s_waitcnt vmcnt(0)
	v_cmp_eq_u32_e32 vcc, v3, v4
	s_and_saveexec_b64 s[14:15], vcc
	s_cbranch_execz .LBB0_153
	s_add_u32 s12, s46, 0x4200
	s_addc_u32 s13, s47, 0
	s_mov_b32 s30, 1
	s_branch .LBB0_146

.LBB0_158:
	s_and_b64 vcc, exec, s[6:7]
	s_cbranch_vccz .LBB0_242
	s_waitcnt vmcnt(0)
	s_barrier
	v_readfirstlane_b32 s98, v0
	s_lshr_b32 s98, s98, 6
	s_cmp_lg_u32 s98, 1
	s_cbranch_scc1 .Linv_skip_3
	buffer_inv sc1
	s_waitcnt vmcnt(0)
.Linv_skip_3:
	s_and_saveexec_b64 s[20:21], s[44:45]
	s_cbranch_execz .LBB0_241
	s_add_i32 s6, 0, 0x24160
	v_mov_b32_e32 v2, s6
	s_waitcnt vmcnt(0) expcnt(0) lgkmcnt(0)
	ds_read_b32 v11, v2
	s_add_i32 s6, 0, 0x24164
	v_mov_b32_e32 v2, s6
	ds_read_b32 v10, v2
	s_waitcnt lgkmcnt(1)
	v_cmp_ne_u32_e32 vcc, 0, v11
	s_cbranch_vccnz .LBB0_175
	v_readlane_b32 s6, v254, 0
	v_readlane_b32 s7, v254, 1
	s_load_dwordx2 s[8:9], s[6:7], 0x4
	s_add_u32 s22, s46, 0x4200
	s_addc_u32 s23, s47, 0
	s_add_u32 s6, s46, 0x4400
	s_addc_u32 s7, s47, 0
	s_waitcnt lgkmcnt(0)
	s_mul_i32 s50, s8, s3
	s_add_u32 s8, s46, 0x4500
	s_mul_i32 s50, s50, s9
	s_addc_u32 s9, s47, 0
	s_add_u32 s10, s46, 0x4600
	s_addc_u32 s11, s47, 0
	s_add_u32 s12, s46, 0x4700
	s_addc_u32 s13, s47, 0
	s_add_u32 s14, s46, 0x4800
	s_addc_u32 s15, s47, 0
	s_add_u32 s16, s46, 0x4900
	s_addc_u32 s17, s47, 0
	s_add_u32 s18, s46, 0x4a00
	s_addc_u32 s19, s47, 0
	s_add_u32 s28, s46, 0x4b00
	s_addc_u32 s29, s47, 0
	s_add_u32 s30, s46, 0x4c00
	s_addc_u32 s31, s47, 0
	s_add_u32 s34, s46, 0x4d00
	s_addc_u32 s35, s47, 0
	s_add_u32 s36, s46, 0x4e00
	s_addc_u32 s37, s47, 0
	s_add_u32 s38, s46, 0x4f00
	s_addc_u32 s39, s47, 0
	s_add_u32 s40, s46, 0x5000
	s_addc_u32 s41, s47, 0
	s_add_u32 s42, s46, 0x5100
	s_addc_u32 s43, s47, 0
	s_add_u32 s56, s46, 0x5200
	s_addc_u32 s57, s47, 0
	s_add_u32 s58, s46, 0x5300
	s_addc_u32 s59, s47, 0
	s_mov_b32 s51, 1
	v_mov_b32_e32 v18, 0
	s_branch .LBB0_163

.LBB0_190:
	s_or_b64 exec, exec, s[10:11]
	s_waitcnt vmcnt(0) lgkmcnt(0)
	s_waitcnt vmcnt(0)

.LBB0_240:
	s_or_b64 exec, exec, s[6:7]
	s_waitcnt vmcnt(0)
	s_waitcnt vmcnt(0)

.LBB0_368:
	s_waitcnt vmcnt(0)
	s_waitcnt vmcnt(0) lgkmcnt(0)
	s_barrier
	v_readfirstlane_b32 s98, v0
	s_lshr_b32 s98, s98, 6
	s_cmp_lg_u32 s98, 1
	s_cbranch_scc1 .Linv_skip_4
	buffer_inv sc1
	s_waitcnt vmcnt(0)
.Linv_skip_4:
	s_and_saveexec_b64 s[22:23], s[44:45]
	s_cbranch_execz .LBB0_450
	s_add_i32 s6, 0, 0x24160
	v_mov_b32_e32 v2, s6
	s_waitcnt vmcnt(0) expcnt(0) lgkmcnt(0)
	ds_read_b32 v11, v2
	s_add_i32 s6, 0, 0x24164
	v_mov_b32_e32 v2, s6
	ds_read_b32 v10, v2
	s_waitcnt lgkmcnt(1)
	v_cmp_ne_u32_e32 vcc, 0, v11
	s_cbranch_vccnz .LBB0_384
	v_readlane_b32 s6, v254, 0
	v_readlane_b32 s7, v254, 1
	s_load_dwordx2 s[10:11], s[6:7], 0x4
	s_add_u32 s28, s46, 0x4200
	s_addc_u32 s29, s47, 0
	s_add_u32 s6, s46, 0x4400
	s_addc_u32 s7, s47, 0
	s_waitcnt lgkmcnt(0)
	s_mul_i32 s50, s10, s3
	s_add_u32 s10, s46, 0x4500
	s_mul_i32 s50, s50, s11
	s_addc_u32 s11, s47, 0
	s_add_u32 s12, s46, 0x4600
	s_addc_u32 s13, s47, 0
	s_add_u32 s14, s46, 0x4700
	s_addc_u32 s15, s47, 0
	s_add_u32 s16, s46, 0x4800
	s_addc_u32 s17, s47, 0
	s_add_u32 s18, s46, 0x4900
	s_addc_u32 s19, s47, 0
	s_add_u32 s20, s46, 0x4a00
	s_addc_u32 s21, s47, 0
	s_add_u32 s30, s46, 0x4b00
	s_addc_u32 s31, s47, 0
	s_add_u32 s34, s46, 0x4c00
	s_addc_u32 s35, s47, 0
	s_add_u32 s36, s46, 0x4d00
	s_addc_u32 s37, s47, 0
	s_add_u32 s38, s46, 0x4e00
	s_addc_u32 s39, s47, 0
	s_add_u32 s40, s46, 0x4f00
	s_addc_u32 s41, s47, 0
	s_add_u32 s42, s46, 0x5000
	s_addc_u32 s43, s47, 0
	s_add_u32 s58, s46, 0x5100
	s_addc_u32 s59, s47, 0
	s_add_u32 s60, s46, 0x5200
	s_addc_u32 s61, s47, 0
	s_add_u32 s62, s46, 0x5300
	s_addc_u32 s63, s47, 0
	s_mov_b32 s51, 1
	v_mov_b32_e32 v18, 0
	s_branch .LBB0_372

.LBB0_399:
	s_or_b64 exec, exec, s[12:13]
	s_waitcnt vmcnt(0) lgkmcnt(0)
	s_waitcnt vmcnt(0)

.LBB0_533:
	s_waitcnt vmcnt(0)
	s_waitcnt lgkmcnt(0)
	s_barrier
	v_readfirstlane_b32 s98, v0
	s_lshr_b32 s98, s98, 6
	s_cmp_lg_u32 s98, 1
	s_cbranch_scc1 .Linv_skip_5
	buffer_inv sc1
	s_waitcnt vmcnt(0)
.Linv_skip_5:
	s_and_saveexec_b64 s[10:11], s[44:45]
	s_cbranch_execz .LBB0_601
	s_add_i32 s12, 0, 0x24160
	v_mov_b32_e32 v2, s12
	s_waitcnt vmcnt(0) expcnt(0) lgkmcnt(0)
	ds_read_b32 v2, v2
	s_mov_b64 s[14:15], exec
	s_lshl_b32 s12, s33, 8
	v_mbcnt_lo_u32_b32 v3, s14, 0
	s_add_u32 s12, s48, s12
	v_mbcnt_hi_u32_b32 v3, s15, v3
	s_addc_u32 s13, s49, 0
	v_cmp_eq_u32_e32 vcc, 0, v3
	s_and_saveexec_b64 s[16:17], vcc
	s_cbranch_execz .LBB0_536
	s_bcnt1_i32_b64 s14, s[14:15]
	v_mov_b32_e32 v4, 0x3000
	v_mov_b32_e32 v5, s14
	global_atomic_add v4, v4, v5, s[12:13] offset:1536 sc0
.LBB0_536:
	s_or_b64 exec, exec, s[16:17]
	s_waitcnt lgkmcnt(0)
	v_cvt_f32_u32_e32 v5, v2
	s_waitcnt vmcnt(0)
	v_readfirstlane_b32 s14, v4
	s_mov_b64 s[16:17], -1
	v_rcp_iflag_f32_e32 v5, v5
	v_add_u32_e32 v3, s14, v3
	v_add_u32_e32 v6, 1, v3
	s_add_u32 s14, s12, 0x4600
	v_mul_f32_e32 v4, 0x4f7ffffe, v5
	v_cvt_u32_f32_e32 v4, v4
	v_sub_u32_e32 v5, 0, v2
	s_addc_u32 s15, s13, 0
	v_mul_lo_u32 v5, v5, v4
	v_mul_hi_u32 v5, v4, v5
	v_add_u32_e32 v4, v4, v5
	v_mul_hi_u32 v4, v3, v4
	v_mul_lo_u32 v5, v4, v2
	v_sub_u32_e32 v3, v3, v5
	v_add_u32_e32 v7, 1, v4
	v_cmp_ge_u32_e32 vcc, v3, v2
	v_sub_u32_e32 v5, v3, v2
	s_nop 0
	v_cndmask_b32_e32 v4, v4, v7, vcc
	v_cndmask_b32_e32 v3, v3, v5, vcc
	v_add_u32_e32 v5, 1, v4
	v_cmp_ge_u32_e32 vcc, v3, v2
	s_nop 1
	v_cndmask_b32_e32 v4, v4, v5, vcc
	v_mul_lo_u32 v3, v2, v4
	v_add_u32_e32 v2, v3, v2
	v_cmp_ne_u32_e32 vcc, v6, v2
	v_mov_b64_e32 v[2:3], s[14:15]
	s_and_saveexec_b64 s[12:13], vcc
	s_cbranch_execz .LBB0_598
	v_mov_b32_e32 v2, 0
	global_load_dword v3, v2, s[14:15] sc1
	s_mov_b64 s[20:21], 0
	s_waitcnt vmcnt(0)
	v_cmp_eq_u32_e32 vcc, v3, v4
	s_and_saveexec_b64 s[18:19], vcc
	s_cbranch_execz .LBB0_597
	s_add_u32 s16, s46, 0x4200
	s_addc_u32 s17, s47, 0
	s_mov_b32 s36, 1
	s_branch .LBB0_540

.Linv_skip_6:
	s_and_saveexec_b64 s[28:29], s[44:45]
	s_cbranch_execz .LBB0_684
	s_add_i32 s10, 0, 0x24160
	v_mov_b32_e32 v2, s10
	s_waitcnt vmcnt(0) expcnt(0) lgkmcnt(0)
	ds_read_b32 v11, v2
	s_add_i32 s10, 0, 0x24164
	v_mov_b32_e32 v2, s10
	ds_read_b32 v10, v2
	s_waitcnt lgkmcnt(1)
	v_cmp_ne_u32_e32 vcc, 0, v11
	s_cbranch_vccnz .LBB0_618
	v_readlane_b32 s10, v254, 0
	v_readlane_b32 s11, v254, 1
	s_load_dwordx2 s[12:13], s[10:11], 0x4
	s_add_u32 s30, s46, 0x4200
	s_addc_u32 s31, s47, 0
	s_add_u32 s10, s46, 0x4400
	s_addc_u32 s11, s47, 0
	s_waitcnt lgkmcnt(0)
	s_mul_i32 s50, s12, s3
	s_add_u32 s12, s46, 0x4500
	s_mul_i32 s50, s50, s13
	s_addc_u32 s13, s47, 0
	s_add_u32 s14, s46, 0x4600
	s_addc_u32 s15, s47, 0
	s_add_u32 s16, s46, 0x4700
	s_addc_u32 s17, s47, 0
	s_add_u32 s18, s46, 0x4800
	s_addc_u32 s19, s47, 0
	s_add_u32 s20, s46, 0x4900
	s_addc_u32 s21, s47, 0
	s_add_u32 s22, s46, 0x4a00
	s_addc_u32 s23, s47, 0
	s_add_u32 s34, s46, 0x4b00
	s_addc_u32 s35, s47, 0
	s_add_u32 s36, s46, 0x4c00
	s_addc_u32 s37, s47, 0
	s_add_u32 s38, s46, 0x4d00
	s_addc_u32 s39, s47, 0
	s_add_u32 s40, s46, 0x4e00
	s_addc_u32 s41, s47, 0
	s_add_u32 s42, s46, 0x4f00
	s_addc_u32 s43, s47, 0
	s_add_u32 s58, s46, 0x5000
	s_addc_u32 s59, s47, 0
	s_add_u32 s60, s46, 0x5100
	s_addc_u32 s61, s47, 0
	s_add_u32 s62, s46, 0x5200
	s_addc_u32 s63, s47, 0
	s_add_u32 s64, s46, 0x5300
	s_addc_u32 s65, s47, 0
	s_mov_b32 s51, 1
	v_mov_b32_e32 v18, 0
	s_branch .LBB0_606

.LBB0_633:
	s_or_b64 exec, exec, s[14:15]
	s_waitcnt vmcnt(0) lgkmcnt(0)
	s_waitcnt vmcnt(0)

.LBB0_683:
	s_or_b64 exec, exec, s[10:11]
	s_waitcnt vmcnt(0)
	s_waitcnt vmcnt(0)

.Linv_skip_7:
	s_and_saveexec_b64 s[22:23], s[44:45]
	s_cbranch_execz .LBB0_841
	s_add_i32 s8, 0, 0x24160
	v_mov_b32_e32 v2, s8
	s_waitcnt vmcnt(0) expcnt(0) lgkmcnt(0)
	ds_read_b32 v11, v2
	s_add_i32 s8, 0, 0x24164
	v_mov_b32_e32 v2, s8
	ds_read_b32 v10, v2
	s_waitcnt lgkmcnt(1)
	v_cmp_ne_u32_e32 vcc, 0, v11
	s_cbranch_vccnz .LBB0_775
	v_readlane_b32 s8, v254, 0
	v_readlane_b32 s9, v254, 1
	s_load_dwordx2 s[10:11], s[8:9], 0x4
	s_add_u32 s24, s46, 0x4200
	s_addc_u32 s25, s47, 0
	s_add_u32 s8, s46, 0x4400
	s_addc_u32 s9, s47, 0
	s_waitcnt lgkmcnt(0)
	s_mul_i32 s50, s10, s3
	s_add_u32 s10, s46, 0x4500
	s_mul_i32 s50, s50, s11
	s_addc_u32 s11, s47, 0
	s_add_u32 s12, s46, 0x4600
	s_addc_u32 s13, s47, 0
	s_add_u32 s14, s46, 0x4700
	s_addc_u32 s15, s47, 0
	s_add_u32 s16, s46, 0x4800
	s_addc_u32 s17, s47, 0
	s_add_u32 s18, s46, 0x4900
	s_addc_u32 s19, s47, 0
	s_add_u32 s20, s46, 0x4a00
	s_addc_u32 s21, s47, 0
	s_add_u32 s28, s46, 0x4b00
	s_addc_u32 s29, s47, 0
	s_add_u32 s30, s46, 0x4c00
	s_addc_u32 s31, s47, 0
	s_add_u32 s34, s46, 0x4d00
	s_addc_u32 s35, s47, 0
	s_add_u32 s36, s46, 0x4e00
	s_addc_u32 s37, s47, 0
	s_add_u32 s38, s46, 0x4f00
	s_addc_u32 s39, s47, 0
	s_add_u32 s40, s46, 0x5000
	s_addc_u32 s41, s47, 0
	s_add_u32 s42, s46, 0x5100
	s_addc_u32 s43, s47, 0
	s_add_u32 s58, s46, 0x5200
	s_addc_u32 s59, s47, 0
	s_add_u32 s60, s46, 0x5300
	s_addc_u32 s61, s47, 0
	s_mov_b32 s51, 1
	v_mov_b32_e32 v18, 0
	s_branch .LBB0_763

.LBB0_840:
	s_or_b64 exec, exec, s[8:9]
	s_waitcnt vmcnt(0)
	s_waitcnt vmcnt(0)

.Linv_skip_8:
	s_and_saveexec_b64 s[22:23], s[44:45]
	s_cbranch_execz .LBB0_964
	s_add_i32 s8, 0, 0x24160
	v_mov_b32_e32 v2, s8
	s_waitcnt vmcnt(0) expcnt(0) lgkmcnt(0)
	ds_read_b32 v11, v2
	s_add_i32 s8, 0, 0x24164
	v_mov_b32_e32 v2, s8
	ds_read_b32 v10, v2
	s_waitcnt lgkmcnt(1)
	v_cmp_ne_u32_e32 vcc, 0, v11
	s_cbranch_vccnz .LBB0_898
	v_readlane_b32 s8, v254, 0
	v_readlane_b32 s9, v254, 1
	s_load_dwordx2 s[10:11], s[8:9], 0x4
	s_add_u32 s24, s46, 0x4200
	s_addc_u32 s25, s47, 0
	s_add_u32 s8, s46, 0x4400
	s_addc_u32 s9, s47, 0
	s_waitcnt lgkmcnt(0)
	s_mul_i32 s50, s10, s3
	s_add_u32 s10, s46, 0x4500
	s_mul_i32 s50, s50, s11
	s_addc_u32 s11, s47, 0
	s_add_u32 s12, s46, 0x4600
	s_addc_u32 s13, s47, 0
	s_add_u32 s14, s46, 0x4700
	s_addc_u32 s15, s47, 0
	s_add_u32 s16, s46, 0x4800
	s_addc_u32 s17, s47, 0
	s_add_u32 s18, s46, 0x4900
	s_addc_u32 s19, s47, 0
	s_add_u32 s20, s46, 0x4a00
	s_addc_u32 s21, s47, 0
	s_add_u32 s26, s46, 0x4b00
	s_addc_u32 s27, s47, 0
	s_add_u32 s28, s46, 0x4c00
	s_addc_u32 s29, s47, 0
	s_add_u32 s30, s46, 0x4d00
	s_addc_u32 s31, s47, 0
	s_add_u32 s34, s46, 0x4e00
	s_addc_u32 s35, s47, 0
	s_add_u32 s36, s46, 0x4f00
	s_addc_u32 s37, s47, 0
	s_add_u32 s38, s46, 0x5000
	s_addc_u32 s39, s47, 0
	s_add_u32 s40, s46, 0x5100
	s_addc_u32 s41, s47, 0
	s_add_u32 s42, s46, 0x5200
	s_addc_u32 s43, s47, 0
	s_add_u32 s58, s46, 0x5300
	s_addc_u32 s59, s47, 0
	s_mov_b32 s51, 1
	v_mov_b32_e32 v18, 0
	s_branch .LBB0_886

.LBB0_1651:
	s_and_b64 vcc, exec, s[4:5]
	s_mov_b64 s[8:9], -1
	s_cbranch_vccnz .LBB0_1671
	s_waitcnt vmcnt(0)
	s_barrier
	v_readfirstlane_b32 s98, v0
	s_lshr_b32 s98, s98, 6
	s_cmp_lg_u32 s98, 1
	s_cbranch_scc1 .Linv_skip_10
	buffer_inv sc1
	s_waitcnt vmcnt(0)
.Linv_skip_10:
	s_and_saveexec_b64 s[8:9], s[44:45]
	s_cbranch_execz .LBB0_1670
	s_add_i32 s10, 0, 0x24160
	s_waitcnt vmcnt(5)
	v_mov_b32_e32 v2, s10
	s_waitcnt vmcnt(0) expcnt(0) lgkmcnt(0)
	ds_read_b32 v2, v2
	s_mov_b64 s[12:13], exec
	s_lshl_b32 s10, s33, 8
	v_mbcnt_lo_u32_b32 v3, s12, 0
	s_add_u32 s10, s48, s10
	v_mbcnt_hi_u32_b32 v3, s13, v3
	s_addc_u32 s11, s49, 0
	v_cmp_eq_u32_e32 vcc, 0, v3
	s_and_saveexec_b64 s[14:15], vcc
	s_cbranch_execz .LBB0_1655
	s_bcnt1_i32_b64 s12, s[12:13]
	v_mov_b32_e32 v4, 0x3000
	v_mov_b32_e32 v5, s12
	global_atomic_add v4, v4, v5, s[10:11] offset:1536 sc0
.LBB0_1655:
	s_or_b64 exec, exec, s[14:15]
	s_waitcnt lgkmcnt(0)
	v_cvt_f32_u32_e32 v5, v2
	s_waitcnt vmcnt(0)
	v_readfirstlane_b32 s12, v4
	s_mov_b64 s[14:15], -1
	v_rcp_iflag_f32_e32 v5, v5
	v_add_u32_e32 v3, s12, v3
	v_add_u32_e32 v6, 1, v3
	s_add_u32 s12, s10, 0x4600
	v_mul_f32_e32 v4, 0x4f7ffffe, v5
	v_cvt_u32_f32_e32 v4, v4
	v_sub_u32_e32 v5, 0, v2
	s_addc_u32 s13, s11, 0
	v_mul_lo_u32 v5, v5, v4
	v_mul_hi_u32 v5, v4, v5
	v_add_u32_e32 v4, v4, v5
	v_mul_hi_u32 v4, v3, v4
	v_mul_lo_u32 v5, v4, v2
	v_sub_u32_e32 v3, v3, v5
	v_add_u32_e32 v7, 1, v4
	v_cmp_ge_u32_e32 vcc, v3, v2
	v_sub_u32_e32 v5, v3, v2
	s_nop 0
	v_cndmask_b32_e32 v4, v4, v7, vcc
	v_cndmask_b32_e32 v3, v3, v5, vcc
	v_add_u32_e32 v5, 1, v4
	v_cmp_ge_u32_e32 vcc, v3, v2
	s_nop 1
	v_cndmask_b32_e32 v4, v4, v5, vcc
	v_mul_lo_u32 v3, v2, v4
	v_add_u32_e32 v2, v3, v2
	v_cmp_ne_u32_e32 vcc, v6, v2
	v_mov_b64_e32 v[2:3], s[12:13]
	s_and_saveexec_b64 s[10:11], vcc
	s_cbranch_execz .LBB0_1667
	v_mov_b32_e32 v2, 0
	global_load_dword v3, v2, s[12:13] sc1
	s_mov_b64 s[18:19], 0
	s_waitcnt vmcnt(0)
	v_cmp_eq_u32_e32 vcc, v3, v4
	s_and_saveexec_b64 s[16:17], vcc
	s_cbranch_execz .LBB0_1666
	s_add_u32 s14, s46, 0x4200
	s_addc_u32 s15, s47, 0
	s_mov_b32 s28, 1
	s_branch .LBB0_1659

.LBB0_1671:
	s_and_b64 vcc, exec, s[8:9]
	s_cbranch_vccz .LBB0_1755
	s_waitcnt vmcnt(0)
	s_barrier
	v_readfirstlane_b32 s98, v0
	s_lshr_b32 s98, s98, 6
	s_cmp_lg_u32 s98, 1
	s_cbranch_scc1 .Linv_skip_11
	buffer_inv sc1
	s_waitcnt vmcnt(0)
.Linv_skip_11:
	s_and_saveexec_b64 s[22:23], s[44:45]
	s_cbranch_execz .LBB0_1754
	s_add_i32 s8, 0, 0x24160
	s_waitcnt vmcnt(5)
	v_mov_b32_e32 v2, s8
	s_waitcnt vmcnt(0) expcnt(0) lgkmcnt(0)
	ds_read_b32 v11, v2
	s_add_i32 s8, 0, 0x24164
	v_mov_b32_e32 v2, s8
	ds_read_b32 v10, v2
	s_waitcnt lgkmcnt(1)
	v_cmp_ne_u32_e32 vcc, 0, v11
	s_cbranch_vccnz .LBB0_1688
	v_readlane_b32 s8, v254, 0
	v_readlane_b32 s9, v254, 1
	s_load_dwordx2 s[10:11], s[8:9], 0x4
	s_add_u32 s24, s46, 0x4200
	s_addc_u32 s25, s47, 0
	s_add_u32 s8, s46, 0x4400
	s_addc_u32 s9, s47, 0
	s_waitcnt lgkmcnt(0)
	s_mul_i32 s50, s10, s3
	s_add_u32 s10, s46, 0x4500
	s_mul_i32 s50, s50, s11
	s_addc_u32 s11, s47, 0
	s_add_u32 s12, s46, 0x4600
	s_addc_u32 s13, s47, 0
	s_add_u32 s14, s46, 0x4700
	s_addc_u32 s15, s47, 0
	s_add_u32 s16, s46, 0x4800
	s_addc_u32 s17, s47, 0
	s_add_u32 s18, s46, 0x4900
	s_addc_u32 s19, s47, 0
	s_add_u32 s20, s46, 0x4a00
	s_addc_u32 s21, s47, 0
	s_add_u32 s26, s46, 0x4b00
	s_addc_u32 s27, s47, 0
	s_add_u32 s28, s46, 0x4c00
	s_addc_u32 s29, s47, 0
	s_add_u32 s30, s46, 0x4d00
	s_addc_u32 s31, s47, 0
	s_add_u32 s34, s46, 0x4e00
	s_addc_u32 s35, s47, 0
	s_add_u32 s36, s46, 0x4f00
	s_addc_u32 s37, s47, 0
	s_add_u32 s38, s46, 0x5000
	s_addc_u32 s39, s47, 0
	s_add_u32 s40, s46, 0x5100
	s_addc_u32 s41, s47, 0
	s_add_u32 s42, s46, 0x5200
	s_addc_u32 s43, s47, 0
	s_add_u32 s54, s46, 0x5300
	s_addc_u32 s55, s47, 0
	s_mov_b32 s51, 1
	v_mov_b32_e32 v18, 0
	s_branch .LBB0_1676

.Linv_skip_12:
	s_and_saveexec_b64 s[8:9], s[44:45]
	s_cbranch_execz .LBB0_1881
	s_add_i32 s10, 0, 0x24160
	v_mov_b32_e32 v2, s10
	s_waitcnt vmcnt(0) expcnt(0) lgkmcnt(0)
	ds_read_b32 v2, v2
	s_mov_b64 s[12:13], exec
	s_lshl_b32 s10, s33, 8
	v_mbcnt_lo_u32_b32 v3, s12, 0
	s_add_u32 s10, s48, s10
	v_mbcnt_hi_u32_b32 v3, s13, v3
	s_addc_u32 s11, s49, 0
	v_cmp_eq_u32_e32 vcc, 0, v3
	s_and_saveexec_b64 s[14:15], vcc
	s_cbranch_execz .LBB0_1816
	s_bcnt1_i32_b64 s12, s[12:13]
	v_mov_b32_e32 v4, 0x3000
	v_mov_b32_e32 v5, s12
	global_atomic_add v4, v4, v5, s[10:11] offset:1536 sc0

.Linv_skip_13:
	s_and_saveexec_b64 s[22:23], s[44:45]
	s_cbranch_execz .LBB0_1964
	s_add_i32 s8, 0, 0x24160
	v_mov_b32_e32 v2, s8
	s_waitcnt vmcnt(0) expcnt(0) lgkmcnt(0)
	ds_read_b32 v11, v2
	s_add_i32 s8, 0, 0x24164
	v_mov_b32_e32 v2, s8
	ds_read_b32 v10, v2
	s_waitcnt lgkmcnt(1)
	v_cmp_ne_u32_e32 vcc, 0, v11
	s_cbranch_vccnz .LBB0_1898
	v_readlane_b32 s8, v254, 0
	v_readlane_b32 s9, v254, 1
	s_load_dwordx2 s[10:11], s[8:9], 0x4
	s_add_u32 s24, s46, 0x4200
	s_addc_u32 s25, s47, 0
	s_add_u32 s8, s46, 0x4400
	s_addc_u32 s9, s47, 0
	s_waitcnt lgkmcnt(0)
	s_mul_i32 s50, s10, s3
	s_add_u32 s10, s46, 0x4500
	s_mul_i32 s50, s50, s11
	s_addc_u32 s11, s47, 0
	s_add_u32 s12, s46, 0x4600
	s_addc_u32 s13, s47, 0
	s_add_u32 s14, s46, 0x4700
	s_addc_u32 s15, s47, 0
	s_add_u32 s16, s46, 0x4800
	s_addc_u32 s17, s47, 0
	s_add_u32 s18, s46, 0x4900
	s_addc_u32 s19, s47, 0
	s_add_u32 s20, s46, 0x4a00
	s_addc_u32 s21, s47, 0
	s_add_u32 s26, s46, 0x4b00
	s_addc_u32 s27, s47, 0
	s_add_u32 s28, s46, 0x4c00
	s_addc_u32 s29, s47, 0
	s_add_u32 s30, s46, 0x4d00
	s_addc_u32 s31, s47, 0
	s_add_u32 s34, s46, 0x4e00
	s_addc_u32 s35, s47, 0
	s_add_u32 s36, s46, 0x4f00
	s_addc_u32 s37, s47, 0
	s_add_u32 s38, s46, 0x5000
	s_addc_u32 s39, s47, 0
	s_add_u32 s40, s46, 0x5100
	s_addc_u32 s41, s47, 0
	s_add_u32 s42, s46, 0x5200
	s_addc_u32 s43, s47, 0
	s_add_u32 s54, s46, 0x5300
	s_addc_u32 s55, s47, 0
	s_mov_b32 s51, 1
	v_mov_b32_e32 v18, 0
	s_branch .LBB0_1886

.LBB0_2001:
	s_waitcnt vmcnt(0)
	s_waitcnt vmcnt(0)
	s_barrier
	v_readfirstlane_b32 s98, v0
	s_lshr_b32 s98, s98, 6
	s_cmp_lg_u32 s98, 1
	s_cbranch_scc1 .Linv_skip_14
	buffer_inv sc1
	s_waitcnt vmcnt(0)
.Linv_skip_14:
	s_and_saveexec_b64 s[4:5], s[44:45]
	s_cbranch_execz .LBB0_2026
	s_add_i32 s8, 0, 0x24160
	v_mov_b32_e32 v2, s8
	s_waitcnt vmcnt(0) expcnt(0) lgkmcnt(0)
	ds_read_b32 v2, v2
	s_mov_b64 s[10:11], exec
	s_lshl_b32 s8, s33, 8
	v_mbcnt_lo_u32_b32 v3, s10, 0
	s_add_u32 s8, s48, s8
	v_mbcnt_hi_u32_b32 v3, s11, v3
	s_addc_u32 s9, s49, 0
	v_cmp_eq_u32_e32 vcc, 0, v3
	s_and_saveexec_b64 s[12:13], vcc
	s_cbranch_execz .LBB0_2004
	s_bcnt1_i32_b64 s10, s[10:11]
	v_mov_b32_e32 v4, 0x3000
	v_mov_b32_e32 v5, s10
	global_atomic_add v4, v4, v5, s[8:9] offset:1536 sc0
.LBB0_2004:
	s_or_b64 exec, exec, s[12:13]
	s_waitcnt lgkmcnt(0)
	v_cvt_f32_u32_e32 v5, v2
	s_waitcnt vmcnt(0)
	v_readfirstlane_b32 s10, v4
	s_mov_b64 s[12:13], -1
	v_rcp_iflag_f32_e32 v5, v5
	v_add_u32_e32 v3, s10, v3
	v_add_u32_e32 v6, 1, v3
	s_add_u32 s10, s8, 0x4600
	v_mul_f32_e32 v4, 0x4f7ffffe, v5
	v_cvt_u32_f32_e32 v4, v4
	v_sub_u32_e32 v5, 0, v2
	s_addc_u32 s11, s9, 0
	v_mul_lo_u32 v5, v5, v4
	v_mul_hi_u32 v5, v4, v5
	v_add_u32_e32 v4, v4, v5
	v_mul_hi_u32 v4, v3, v4
	v_mul_lo_u32 v5, v4, v2
	v_sub_u32_e32 v3, v3, v5
	v_add_u32_e32 v7, 1, v4
	v_cmp_ge_u32_e32 vcc, v3, v2
	v_sub_u32_e32 v5, v3, v2
	s_nop 0
	v_cndmask_b32_e32 v4, v4, v7, vcc
	v_cndmask_b32_e32 v3, v3, v5, vcc
	v_add_u32_e32 v5, 1, v4
	v_cmp_ge_u32_e32 vcc, v3, v2
	s_nop 1
	v_cndmask_b32_e32 v4, v4, v5, vcc
	v_mul_lo_u32 v3, v2, v4
	v_add_u32_e32 v2, v3, v2
	v_cmp_ne_u32_e32 vcc, v6, v2
	v_mov_b64_e32 v[2:3], s[10:11]
	s_and_saveexec_b64 s[8:9], vcc
	s_cbranch_execz .LBB0_2023
	v_mov_b32_e32 v2, 0
	global_load_dword v3, v2, s[10:11] sc1
	s_mov_b64 s[16:17], 0
	s_waitcnt vmcnt(0)
	v_cmp_eq_u32_e32 vcc, v3, v4
	s_and_saveexec_b64 s[14:15], vcc
	s_cbranch_execz .LBB0_2022
	s_add_u32 s12, s46, 0x4200
	s_addc_u32 s13, s47, 0
	s_mov_b32 s26, 1
	s_branch .LBB0_2008

.Linv_skip_15:
	s_and_saveexec_b64 s[20:21], s[44:45]
	s_cbranch_execz .LBB0_2109
	s_add_i32 s4, 0, 0x24160
	v_mov_b32_e32 v2, s4
	s_waitcnt vmcnt(0) expcnt(0) lgkmcnt(0)
	ds_read_b32 v11, v2
	s_add_i32 s4, 0, 0x24164
	v_mov_b32_e32 v2, s4
	ds_read_b32 v10, v2
	s_waitcnt lgkmcnt(1)
	v_cmp_ne_u32_e32 vcc, 0, v11
	s_cbranch_vccnz .LBB0_2043
	v_readlane_b32 s4, v254, 0
	v_readlane_b32 s5, v254, 1
	s_load_dwordx2 s[8:9], s[4:5], 0x4
	s_add_u32 s22, s46, 0x4200
	s_addc_u32 s23, s47, 0
	s_add_u32 s4, s46, 0x4400
	s_addc_u32 s5, s47, 0
	s_waitcnt lgkmcnt(0)
	s_mul_i32 s54, s8, s3
	s_add_u32 s8, s46, 0x4500
	s_mul_i32 s54, s54, s9
	s_addc_u32 s9, s47, 0
	s_add_u32 s10, s46, 0x4600
	s_addc_u32 s11, s47, 0
	s_add_u32 s12, s46, 0x4700
	s_addc_u32 s13, s47, 0
	s_add_u32 s14, s46, 0x4800
	s_addc_u32 s15, s47, 0
	s_add_u32 s16, s46, 0x4900
	s_addc_u32 s17, s47, 0
	s_add_u32 s18, s46, 0x4a00
	s_addc_u32 s19, s47, 0
	s_add_u32 s24, s46, 0x4b00
	s_addc_u32 s25, s47, 0
	s_add_u32 s26, s46, 0x4c00
	s_addc_u32 s27, s47, 0
	s_add_u32 s28, s46, 0x4d00
	s_addc_u32 s29, s47, 0
	s_add_u32 s30, s46, 0x4e00
	s_addc_u32 s31, s47, 0
	s_add_u32 s34, s46, 0x4f00
	s_addc_u32 s35, s47, 0
	s_add_u32 s36, s46, 0x5000
	s_addc_u32 s37, s47, 0
	s_add_u32 s38, s46, 0x5100
	s_addc_u32 s39, s47, 0
	s_add_u32 s40, s46, 0x5200
	s_addc_u32 s41, s47, 0
	s_add_u32 s42, s46, 0x5300
	s_addc_u32 s43, s47, 0
	s_mov_b32 s55, 1
	v_mov_b32_e32 v18, 0
	s_branch .LBB0_2031

	.amdhsa_kernel _Z9hymba_fwd4Args
		.amdhsa_group_segment_fixed_size 0
		.amdhsa_private_segment_fixed_size 0
		.amdhsa_kernarg_size 408
		.amdhsa_user_sgpr_count 2
		.amdhsa_user_sgpr_dispatch_ptr 0
		.amdhsa_user_sgpr_queue_ptr 0
		.amdhsa_user_sgpr_kernarg_segment_ptr 1
		.amdhsa_user_sgpr_dispatch_id 0
		.amdhsa_user_sgpr_kernarg_preload_length 0
		.amdhsa_user_sgpr_kernarg_preload_offset 0
		.amdhsa_user_sgpr_private_segment_size 0
		.amdhsa_uses_dynamic_stack 0
		.amdhsa_enable_private_segment 0
		.amdhsa_system_sgpr_workgroup_id_x 1
		.amdhsa_system_sgpr_workgroup_id_y 0
		.amdhsa_system_sgpr_workgroup_id_z 0
		.amdhsa_system_sgpr_workgroup_info 0
		.amdhsa_system_vgpr_workitem_id 0
		.amdhsa_next_free_vgpr 255
		.amdhsa_next_free_sgpr 100
		.amdhsa_accum_offset 256
		.amdhsa_reserve_vcc 1
		.amdhsa_float_round_mode_32 0
		.amdhsa_float_round_mode_16_64 0
		.amdhsa_float_denorm_mode_32 3
		.amdhsa_float_denorm_mode_16_64 3
		.amdhsa_dx10_clamp 1
		.amdhsa_ieee_mode 1
		.amdhsa_fp16_overflow 0
		.amdhsa_tg_split 0
		.amdhsa_exception_fp_ieee_invalid_op 0
		.amdhsa_exception_fp_denorm_src 0
		.amdhsa_exception_fp_ieee_div_zero 0
		.amdhsa_exception_fp_ieee_overflow 0
		.amdhsa_exception_fp_ieee_underflow 0
		.amdhsa_exception_fp_ieee_inexact 0
		.amdhsa_exception_int_div_zero 0
	.end_amdhsa_kernel

amdhsa.kernels:
  - .agpr_count:     0
    .args:
      - .offset:         0
        .size:           152
        .value_kind:     by_value
      - .offset:         152
        .size:           4
        .value_kind:     hidden_block_count_x
      - .offset:         156
        .size:           4
        .value_kind:     hidden_block_count_y
      - .offset:         160
        .size:           4
        .value_kind:     hidden_block_count_z
      - .offset:         164
        .size:           2
        .value_kind:     hidden_group_size_x
      - .offset:         166
        .size:           2
        .value_kind:     hidden_group_size_y
      - .offset:         168
        .size:           2
        .value_kind:     hidden_group_size_z
      - .offset:         170
        .size:           2
        .value_kind:     hidden_remainder_x
      - .offset:         172
        .size:           2
        .value_kind:     hidden_remainder_y
      - .offset:         174
        .size:           2
        .value_kind:     hidden_remainder_z
      - .offset:         192
        .size:           8
        .value_kind:     hidden_global_offset_x
      - .offset:         200
        .size:           8
        .value_kind:     hidden_global_offset_y
      - .offset:         208
        .size:           8
        .value_kind:     hidden_global_offset_z
      - .offset:         216
        .size:           2
        .value_kind:     hidden_grid_dims
      - .offset:         272
        .size:           4
        .value_kind:     hidden_dynamic_lds_size
    .group_segment_fixed_size: 0
    .kernarg_segment_align: 8
    .kernarg_segment_size: 408
    .language:       OpenCL C
    .language_version:
      - 2
      - 0
    .max_flat_workgroup_size: 512
    .name:           _Z9hymba_fwd4Args
    .private_segment_fixed_size: 0
    .sgpr_count:     106
    .sgpr_spill_count: 4
    .symbol:         _Z9hymba_fwd4Args.kd
    .uniform_work_group_size: 1
    .uses_dynamic_stack: false
    .vgpr_count:     255
    .vgpr_spill_count: 0
    .wavefront_size: 64
